# v031: kind-8 GEMM epilogue, f32-residual mode (layer-0 mix-out): residual loads of the first 8 groups run 4 groups ahead with counted waits instead of one load+vmcnt(0) per group
# baseline (speedup 1.0000x reference)
.LBB0_1166:
	v_lshlrev_b64 v[160:161], 10, v[180:181]
	v_lshl_add_u64 v[176:177], v[174:175], 0, s[4:5]
	v_lshl_add_u64 v[168:169], v[176:177], 0, v[160:161]
	v_cndmask_b32_e64 v160, 0, 1, s[20:21]
	v_cmp_ne_u32_e64 s[0:1], 1, v160
	s_andn2_b64 vcc, exec, s[20:21]
	v_lshl_add_u64 v[184:185], v[168:169], 2, s[64:65]
	s_cbranch_vccnz .LBB0_1242
	v_mov_b32_e32 v190, v184
	v_mov_b32_e32 v191, v185
	v_mov_b32_e32 v213, 0
	v_mov_b32_e32 v212, 0
	v_lshl_add_u64 v[246:247], v[212:213], 0, v[190:191]
	global_load_dwordx4 v[128:131], v[246:247], off
	global_load_dwordx4 v[132:135], v[246:247], off offset:16
	v_mov_b32_e32 v212, 0x200
	v_lshl_add_u64 v[246:247], v[212:213], 0, v[190:191]
	global_load_dwordx4 v[136:139], v[246:247], off
	global_load_dwordx4 v[140:143], v[246:247], off offset:16
	v_mov_b32_e32 v212, 0x10000
	v_lshl_add_u64 v[246:247], v[212:213], 0, v[190:191]
	global_load_dwordx4 v[144:147], v[246:247], off
	global_load_dwordx4 v[148:151], v[246:247], off offset:16
	v_mov_b32_e32 v212, 0x10200
	v_lshl_add_u64 v[246:247], v[212:213], 0, v[190:191]
	global_load_dwordx4 v[152:155], v[246:247], off
	global_load_dwordx4 v[156:159], v[246:247], off offset:16
	s_waitcnt vmcnt(6)
	v_mov_b32_e32 v160, v128
	v_mov_b32_e32 v161, v129
	v_mov_b32_e32 v162, v130
	v_mov_b32_e32 v163, v131
	v_mov_b32_e32 v164, v132
	v_mov_b32_e32 v165, v133
	v_mov_b32_e32 v166, v134
	v_mov_b32_e32 v167, v135
	v_mov_b32_e32 v212, 0x20000
	v_lshl_add_u64 v[246:247], v[212:213], 0, v[190:191]
	global_load_dwordx4 v[128:131], v[246:247], off
	global_load_dwordx4 v[132:135], v[246:247], off offset:16
	s_cbranch_execnz .LBB0_1169

.LBB0_1169:
	s_waitcnt lgkmcnt(0)
	v_pk_add_f32 v[162:163], v[126:127], v[162:163]
	v_pk_add_f32 v[160:161], v[124:125], v[160:161]
	v_pk_add_f32 v[166:167], v[122:123], v[166:167]
	v_pk_add_f32 v[164:165], v[120:121], v[164:165]
	v_lshl_add_u64 v[182:183], v[168:169], 1, s[24:25]
	v_cvt_pk_bf16_f32 v168, v160, v161
	v_cvt_pk_bf16_f32 v169, v162, v163
	v_cvt_pk_bf16_f32 v170, v164, v165
	v_cvt_pk_bf16_f32 v171, v166, v167
	s_and_b64 vcc, exec, s[0:1]
	global_store_dwordx4 v[182:183], v[168:171], off
	s_cbranch_vccnz .LBB0_1243
	s_waitcnt vmcnt(7)
	v_mov_b32_e32 v160, v136
	v_mov_b32_e32 v161, v137
	v_mov_b32_e32 v162, v138
	v_mov_b32_e32 v163, v139
	v_mov_b32_e32 v164, v140
	v_mov_b32_e32 v165, v141
	v_mov_b32_e32 v166, v142
	v_mov_b32_e32 v167, v143
	v_mov_b32_e32 v212, 0x20200
	v_lshl_add_u64 v[246:247], v[212:213], 0, v[190:191]
	global_load_dwordx4 v[136:139], v[246:247], off
	global_load_dwordx4 v[140:143], v[246:247], off offset:16
	s_cbranch_execnz .LBB0_1172

.LBB0_1172:
	v_lshlrev_b32_e32 v173, 16, v168
	v_and_b32_e32 v168, 0xffff0000, v168
	v_lshlrev_b32_e32 v175, 16, v169
	v_and_b32_e32 v169, 0xffff0000, v169
	v_mul_f32_e32 v168, v168, v168
	v_mul_f32_e32 v169, v169, v169
	v_lshlrev_b32_e32 v184, 16, v170
	v_and_b32_e32 v170, 0xffff0000, v170
	v_fmac_f32_e32 v168, v173, v173
	v_fmac_f32_e32 v169, v175, v175
	v_add_f32_e32 v168, v168, v169
	v_mul_f32_e32 v169, v170, v170
	v_lshlrev_b32_e32 v185, 16, v171
	v_and_b32_e32 v171, 0xffff0000, v171
	v_fmac_f32_e32 v169, v184, v184
	v_add_f32_e32 v168, v169, v168
	v_mul_f32_e32 v169, v171, v171
	v_fmac_f32_e32 v169, v185, v185
	v_cmp_lt_i32_e32 vcc, v223, v218
	v_add_f32_e32 v170, v169, v168
	s_waitcnt lgkmcnt(0)
	v_pk_add_f32 v[160:161], v[92:93], v[160:161]
	v_cndmask_b32_e32 v168, v217, v223, vcc
	v_lshlrev_b32_e32 v173, 2, v168
	v_pk_add_f32 v[168:169], v[94:95], v[162:163]
	v_cvt_pk_bf16_f32 v162, v160, v161
	v_pk_add_f32 v[166:167], v[90:91], v[166:167]
	v_pk_add_f32 v[164:165], v[88:89], v[164:165]
	v_cvt_pk_bf16_f32 v163, v168, v169
	v_and_b32_e32 v161, 0xffff0000, v162
	v_cvt_pk_bf16_f32 v164, v164, v165
	v_cvt_pk_bf16_f32 v165, v166, v167
	v_lshlrev_b32_e32 v160, 16, v162
	v_and_b32_e32 v167, 0xffff0000, v163
	v_mul_f32_e32 v161, v161, v161
	v_lshlrev_b32_e32 v166, 16, v163
	v_fmac_f32_e32 v161, v160, v160
	v_mul_f32_e32 v160, v167, v167
	v_and_b32_e32 v169, 0xffff0000, v164
	v_fmac_f32_e32 v160, v166, v166
	v_lshlrev_b32_e32 v168, 16, v164
	v_add_f32_e32 v160, v161, v160
	v_mul_f32_e32 v161, v169, v169
	v_and_b32_e32 v175, 0xffff0000, v165
	v_fmac_f32_e32 v161, v168, v168
	v_lshlrev_b32_e32 v171, 16, v165
	v_add_f32_e32 v160, v161, v160
	v_mul_f32_e32 v161, v175, v175
	v_fmac_f32_e32 v161, v171, v171
	v_add_f32_e32 v160, v161, v160
	v_add_f32_e32 v160, v170, v160
	ds_bpermute_b32 v161, v173, v160
	v_cmp_lt_i32_e32 vcc, v224, v218
	global_store_dwordx4 v[182:183], v[162:165], off offset:256
	s_waitcnt lgkmcnt(0)
	v_add_f32_e32 v160, v160, v161
	v_cndmask_b32_e32 v166, v217, v224, vcc
	v_lshlrev_b32_e32 v175, 2, v166
	ds_bpermute_b32 v161, v175, v160
	s_and_saveexec_b64 s[20:21], s[40:41]
	s_cbranch_execz .LBB0_1174
	s_waitcnt lgkmcnt(0)
	v_add_f32_e32 v162, v160, v161
	s_lshl_b32 s16, s75, 2
	v_lshlrev_b64 v[160:161], 6, v[180:181]
	s_ashr_i32 s17, s16, 31
	v_lshl_add_u64 v[160:161], s[26:27], 0, v[160:161]
	v_lshl_add_u64 v[160:161], s[16:17], 2, v[160:161]
	s_lshl_b32 s82, s56, 2
	v_lshl_add_u64 v[160:161], v[160:161], 0, s[82:83]
	global_store_dword v[160:161], v162, off
.LBB0_1174:
	s_or_b64 exec, exec, s[20:21]
	s_or_b32 s5, s63, 16
	v_add_u32_e32 v180, s5, v172
	v_ashrrev_i32_e32 v181, 31, v180
	s_waitcnt lgkmcnt(0)
	v_lshlrev_b64 v[160:161], 10, v[180:181]
	v_lshl_add_u64 v[168:169], v[160:161], 0, v[176:177]
	s_and_b64 vcc, exec, s[0:1]
	v_lshl_add_u64 v[184:185], v[168:169], 2, s[64:65]
	s_cbranch_vccnz .LBB0_1244
	s_waitcnt vmcnt(8)
	v_mov_b32_e32 v160, v144
	v_mov_b32_e32 v161, v145
	v_mov_b32_e32 v162, v146
	v_mov_b32_e32 v163, v147
	v_mov_b32_e32 v164, v148
	v_mov_b32_e32 v165, v149
	v_mov_b32_e32 v166, v150
	v_mov_b32_e32 v167, v151
	v_mov_b32_e32 v212, 0x30000
	v_lshl_add_u64 v[246:247], v[212:213], 0, v[190:191]
	global_load_dwordx4 v[144:147], v[246:247], off
	global_load_dwordx4 v[148:151], v[246:247], off offset:16
	s_cbranch_execnz .LBB0_1177

.LBB0_1177:
	s_waitcnt lgkmcnt(0)
	v_pk_add_f32 v[162:163], v[118:119], v[162:163]
	v_pk_add_f32 v[160:161], v[116:117], v[160:161]
	v_pk_add_f32 v[166:167], v[114:115], v[166:167]
	v_pk_add_f32 v[164:165], v[112:113], v[164:165]
	v_lshl_add_u64 v[182:183], v[168:169], 1, s[24:25]
	v_cvt_pk_bf16_f32 v168, v160, v161
	v_cvt_pk_bf16_f32 v169, v162, v163
	v_cvt_pk_bf16_f32 v170, v164, v165
	v_cvt_pk_bf16_f32 v171, v166, v167
	s_and_b64 vcc, exec, s[0:1]
	global_store_dwordx4 v[182:183], v[168:171], off
	s_cbranch_vccnz .LBB0_1245
	s_waitcnt vmcnt(9)
	v_mov_b32_e32 v160, v152
	v_mov_b32_e32 v161, v153
	v_mov_b32_e32 v162, v154
	v_mov_b32_e32 v163, v155
	v_mov_b32_e32 v164, v156
	v_mov_b32_e32 v165, v157
	v_mov_b32_e32 v166, v158
	v_mov_b32_e32 v167, v159
	v_mov_b32_e32 v212, 0x30200
	v_lshl_add_u64 v[246:247], v[212:213], 0, v[190:191]
	global_load_dwordx4 v[152:155], v[246:247], off
	global_load_dwordx4 v[156:159], v[246:247], off offset:16
	s_cbranch_execnz .LBB0_1180

.LBB0_1180:
	v_lshlrev_b32_e32 v184, 16, v168
	v_and_b32_e32 v168, 0xffff0000, v168
	v_lshlrev_b32_e32 v185, 16, v169
	v_and_b32_e32 v169, 0xffff0000, v169
	v_mul_f32_e32 v168, v168, v168
	v_mul_f32_e32 v169, v169, v169
	v_lshlrev_b32_e32 v186, 16, v170
	v_and_b32_e32 v170, 0xffff0000, v170
	v_fmac_f32_e32 v168, v184, v184
	v_fmac_f32_e32 v169, v185, v185
	v_add_f32_e32 v168, v168, v169
	v_mul_f32_e32 v169, v170, v170
	v_lshlrev_b32_e32 v187, 16, v171
	v_and_b32_e32 v171, 0xffff0000, v171
	v_fmac_f32_e32 v169, v186, v186
	v_add_f32_e32 v168, v169, v168
	v_mul_f32_e32 v169, v171, v171
	v_fmac_f32_e32 v169, v187, v187
	s_waitcnt lgkmcnt(0)
	v_pk_add_f32 v[160:161], v[84:85], v[160:161]
	v_add_f32_e32 v170, v169, v168
	v_pk_add_f32 v[168:169], v[86:87], v[162:163]
	v_cvt_pk_bf16_f32 v162, v160, v161
	v_pk_add_f32 v[166:167], v[82:83], v[166:167]
	v_pk_add_f32 v[164:165], v[80:81], v[164:165]
	v_cvt_pk_bf16_f32 v163, v168, v169
	v_and_b32_e32 v161, 0xffff0000, v162
	v_cvt_pk_bf16_f32 v164, v164, v165
	v_cvt_pk_bf16_f32 v165, v166, v167
	v_lshlrev_b32_e32 v160, 16, v162
	v_and_b32_e32 v167, 0xffff0000, v163
	v_mul_f32_e32 v161, v161, v161
	v_lshlrev_b32_e32 v166, 16, v163
	v_fmac_f32_e32 v161, v160, v160
	v_mul_f32_e32 v160, v167, v167
	v_and_b32_e32 v169, 0xffff0000, v164
	v_fmac_f32_e32 v160, v166, v166
	v_lshlrev_b32_e32 v168, 16, v164
	v_add_f32_e32 v160, v161, v160
	v_mul_f32_e32 v161, v169, v169
	v_and_b32_e32 v184, 0xffff0000, v165
	v_fmac_f32_e32 v161, v168, v168
	v_lshlrev_b32_e32 v171, 16, v165
	v_add_f32_e32 v160, v161, v160
	v_mul_f32_e32 v161, v184, v184
	v_fmac_f32_e32 v161, v171, v171
	v_add_f32_e32 v160, v161, v160
	v_add_f32_e32 v160, v170, v160
	ds_bpermute_b32 v161, v173, v160
	global_store_dwordx4 v[182:183], v[162:165], off offset:256
	s_waitcnt lgkmcnt(0)
	v_add_f32_e32 v160, v160, v161
	ds_bpermute_b32 v161, v175, v160
	s_and_saveexec_b64 s[20:21], s[40:41]
	s_cbranch_execz .LBB0_1182
	s_waitcnt lgkmcnt(0)
	v_add_f32_e32 v162, v160, v161
	s_lshl_b32 s16, s75, 2
	v_lshlrev_b64 v[160:161], 6, v[180:181]
	s_ashr_i32 s17, s16, 31
	v_lshl_add_u64 v[160:161], s[26:27], 0, v[160:161]
	v_lshl_add_u64 v[160:161], s[16:17], 2, v[160:161]
	s_lshl_b32 s82, s56, 2
	v_lshl_add_u64 v[160:161], v[160:161], 0, s[82:83]
	global_store_dword v[160:161], v162, off

.LBB0_1184:
	s_or_b32 s16, s63, 32
	v_add_u32_e32 v180, s16, v172
	v_ashrrev_i32_e32 v181, 31, v180
	s_waitcnt lgkmcnt(0)
	v_lshlrev_b64 v[160:161], 10, v[180:181]
	v_lshl_add_u64 v[168:169], v[160:161], 0, v[176:177]
	s_and_b64 vcc, exec, s[0:1]
	v_lshl_add_u64 v[184:185], v[168:169], 2, s[64:65]
	s_cbranch_vccnz .LBB0_1246
	s_waitcnt vmcnt(10)
	v_mov_b32_e32 v160, v128
	v_mov_b32_e32 v161, v129
	v_mov_b32_e32 v162, v130
	v_mov_b32_e32 v163, v131
	v_mov_b32_e32 v164, v132
	v_mov_b32_e32 v165, v133
	v_mov_b32_e32 v166, v134
	v_mov_b32_e32 v167, v135
	s_cbranch_execnz .LBB0_1187

.LBB0_1187:
	s_waitcnt lgkmcnt(0)
	v_pk_add_f32 v[162:163], v[110:111], v[162:163]
	v_pk_add_f32 v[160:161], v[108:109], v[160:161]
	v_pk_add_f32 v[166:167], v[106:107], v[166:167]
	v_pk_add_f32 v[164:165], v[104:105], v[164:165]
	v_lshl_add_u64 v[182:183], v[168:169], 1, s[24:25]
	v_cvt_pk_bf16_f32 v168, v160, v161
	v_cvt_pk_bf16_f32 v169, v162, v163
	v_cvt_pk_bf16_f32 v170, v164, v165
	v_cvt_pk_bf16_f32 v171, v166, v167
	s_and_b64 vcc, exec, s[0:1]
	global_store_dwordx4 v[182:183], v[168:171], off
	s_cbranch_vccnz .LBB0_1247
	s_waitcnt vmcnt(8)
	v_mov_b32_e32 v160, v136
	v_mov_b32_e32 v161, v137
	v_mov_b32_e32 v162, v138
	v_mov_b32_e32 v163, v139
	v_mov_b32_e32 v164, v140
	v_mov_b32_e32 v165, v141
	v_mov_b32_e32 v166, v142
	v_mov_b32_e32 v167, v143
	s_cbranch_execnz .LBB0_1190

.LBB0_1190:
	v_lshlrev_b32_e32 v184, 16, v168
	v_and_b32_e32 v168, 0xffff0000, v168
	v_lshlrev_b32_e32 v185, 16, v169
	v_and_b32_e32 v169, 0xffff0000, v169
	v_mul_f32_e32 v168, v168, v168
	v_mul_f32_e32 v169, v169, v169
	v_lshlrev_b32_e32 v186, 16, v170
	v_and_b32_e32 v170, 0xffff0000, v170
	v_fmac_f32_e32 v168, v184, v184
	v_fmac_f32_e32 v169, v185, v185
	v_add_f32_e32 v168, v168, v169
	v_mul_f32_e32 v169, v170, v170
	v_lshlrev_b32_e32 v187, 16, v171
	v_and_b32_e32 v171, 0xffff0000, v171
	v_fmac_f32_e32 v169, v186, v186
	v_add_f32_e32 v168, v169, v168
	v_mul_f32_e32 v169, v171, v171
	v_fmac_f32_e32 v169, v187, v187
	s_waitcnt lgkmcnt(0)
	v_pk_add_f32 v[160:161], v[76:77], v[160:161]
	v_add_f32_e32 v170, v169, v168
	v_pk_add_f32 v[168:169], v[78:79], v[162:163]
	v_cvt_pk_bf16_f32 v162, v160, v161
	v_pk_add_f32 v[166:167], v[74:75], v[166:167]
	v_pk_add_f32 v[164:165], v[72:73], v[164:165]
	v_cvt_pk_bf16_f32 v163, v168, v169
	v_and_b32_e32 v161, 0xffff0000, v162
	v_cvt_pk_bf16_f32 v164, v164, v165
	v_cvt_pk_bf16_f32 v165, v166, v167
	v_lshlrev_b32_e32 v160, 16, v162
	v_and_b32_e32 v167, 0xffff0000, v163
	v_mul_f32_e32 v161, v161, v161
	v_lshlrev_b32_e32 v166, 16, v163
	v_fmac_f32_e32 v161, v160, v160
	v_mul_f32_e32 v160, v167, v167
	v_and_b32_e32 v169, 0xffff0000, v164
	v_fmac_f32_e32 v160, v166, v166
	v_lshlrev_b32_e32 v168, 16, v164
	v_add_f32_e32 v160, v161, v160
	v_mul_f32_e32 v161, v169, v169
	v_and_b32_e32 v184, 0xffff0000, v165
	v_fmac_f32_e32 v161, v168, v168
	v_lshlrev_b32_e32 v171, 16, v165
	v_add_f32_e32 v160, v161, v160
	v_mul_f32_e32 v161, v184, v184
	v_fmac_f32_e32 v161, v171, v171
	v_add_f32_e32 v160, v161, v160
	v_add_f32_e32 v160, v170, v160
	ds_bpermute_b32 v161, v173, v160
	global_store_dwordx4 v[182:183], v[162:165], off offset:256
	s_waitcnt lgkmcnt(0)
	v_add_f32_e32 v160, v160, v161
	ds_bpermute_b32 v161, v175, v160
	s_and_saveexec_b64 s[20:21], s[40:41]
	s_cbranch_execz .LBB0_1192
	s_waitcnt lgkmcnt(0)
	v_add_f32_e32 v162, v160, v161
	s_lshl_b32 s54, s75, 2
	v_lshlrev_b64 v[160:161], 6, v[180:181]
	s_ashr_i32 s55, s54, 31
	v_lshl_add_u64 v[160:161], s[26:27], 0, v[160:161]
	v_lshl_add_u64 v[160:161], s[54:55], 2, v[160:161]
	s_lshl_b32 s82, s56, 2
	v_lshl_add_u64 v[160:161], v[160:161], 0, s[82:83]
	global_store_dword v[160:161], v162, off
.LBB0_1192:
	s_or_b64 exec, exec, s[20:21]
	s_or_b32 s17, s63, 48
	v_add_u32_e32 v180, s17, v172
	v_ashrrev_i32_e32 v181, 31, v180
	s_waitcnt lgkmcnt(0)
	v_lshlrev_b64 v[160:161], 10, v[180:181]
	v_lshl_add_u64 v[168:169], v[160:161], 0, v[176:177]
	s_and_b64 vcc, exec, s[0:1]
	v_lshl_add_u64 v[184:185], v[168:169], 2, s[64:65]
	s_cbranch_vccnz .LBB0_1248
	s_waitcnt vmcnt(6)
	v_mov_b32_e32 v160, v144
	v_mov_b32_e32 v161, v145
	v_mov_b32_e32 v162, v146
	v_mov_b32_e32 v163, v147
	v_mov_b32_e32 v164, v148
	v_mov_b32_e32 v165, v149
	v_mov_b32_e32 v166, v150
	v_mov_b32_e32 v167, v151
	s_cbranch_execnz .LBB0_1195

.LBB0_1195:
	s_waitcnt lgkmcnt(0)
	v_pk_add_f32 v[162:163], v[102:103], v[162:163]
	v_pk_add_f32 v[160:161], v[100:101], v[160:161]
	v_pk_add_f32 v[166:167], v[98:99], v[166:167]
	v_pk_add_f32 v[164:165], v[96:97], v[164:165]
	v_lshl_add_u64 v[182:183], v[168:169], 1, s[24:25]
	v_cvt_pk_bf16_f32 v168, v160, v161
	v_cvt_pk_bf16_f32 v169, v162, v163
	v_cvt_pk_bf16_f32 v170, v164, v165
	v_cvt_pk_bf16_f32 v171, v166, v167
	s_and_b64 vcc, exec, s[0:1]
	global_store_dwordx4 v[182:183], v[168:171], off
	s_cbranch_vccnz .LBB0_1249
	s_waitcnt vmcnt(4)
	v_mov_b32_e32 v160, v152
	v_mov_b32_e32 v161, v153
	v_mov_b32_e32 v162, v154
	v_mov_b32_e32 v163, v155
	v_mov_b32_e32 v164, v156
	v_mov_b32_e32 v165, v157
	v_mov_b32_e32 v166, v158
	v_mov_b32_e32 v167, v159
	s_cbranch_execnz .LBB0_1198

.LBB0_1198:
	v_lshlrev_b32_e32 v184, 16, v168
	v_and_b32_e32 v168, 0xffff0000, v168
	v_lshlrev_b32_e32 v185, 16, v169
	v_and_b32_e32 v169, 0xffff0000, v169
	v_mul_f32_e32 v168, v168, v168
	v_mul_f32_e32 v169, v169, v169
	v_lshlrev_b32_e32 v186, 16, v170
	v_and_b32_e32 v170, 0xffff0000, v170
	v_fmac_f32_e32 v168, v184, v184
	v_fmac_f32_e32 v169, v185, v185
	v_add_f32_e32 v168, v168, v169
	v_mul_f32_e32 v169, v170, v170
	v_lshlrev_b32_e32 v187, 16, v171
	v_and_b32_e32 v171, 0xffff0000, v171
	v_fmac_f32_e32 v169, v186, v186
	v_add_f32_e32 v168, v169, v168
	v_mul_f32_e32 v169, v171, v171
	v_fmac_f32_e32 v169, v187, v187
	s_waitcnt lgkmcnt(0)
	v_pk_add_f32 v[160:161], v[68:69], v[160:161]
	v_add_f32_e32 v170, v169, v168
	v_pk_add_f32 v[168:169], v[70:71], v[162:163]
	v_cvt_pk_bf16_f32 v162, v160, v161
	v_pk_add_f32 v[166:167], v[66:67], v[166:167]
	v_pk_add_f32 v[164:165], v[64:65], v[164:165]
	v_cvt_pk_bf16_f32 v163, v168, v169
	v_and_b32_e32 v161, 0xffff0000, v162
	v_cvt_pk_bf16_f32 v164, v164, v165
	v_cvt_pk_bf16_f32 v165, v166, v167
	v_lshlrev_b32_e32 v160, 16, v162
	v_and_b32_e32 v167, 0xffff0000, v163
	v_mul_f32_e32 v161, v161, v161
	v_lshlrev_b32_e32 v166, 16, v163
	v_fmac_f32_e32 v161, v160, v160
	v_mul_f32_e32 v160, v167, v167
	v_and_b32_e32 v169, 0xffff0000, v164
	v_fmac_f32_e32 v160, v166, v166
	v_lshlrev_b32_e32 v168, 16, v164
	v_add_f32_e32 v160, v161, v160
	v_mul_f32_e32 v161, v169, v169
	v_and_b32_e32 v184, 0xffff0000, v165
	v_fmac_f32_e32 v161, v168, v168
	v_lshlrev_b32_e32 v171, 16, v165
	v_add_f32_e32 v160, v161, v160
	v_mul_f32_e32 v161, v184, v184
	v_fmac_f32_e32 v161, v171, v171
	v_add_f32_e32 v160, v161, v160
	v_add_f32_e32 v160, v170, v160
	ds_bpermute_b32 v161, v173, v160
	global_store_dwordx4 v[182:183], v[162:165], off offset:256
	s_waitcnt lgkmcnt(0)
	v_add_f32_e32 v160, v160, v161
	ds_bpermute_b32 v161, v175, v160
	s_and_saveexec_b64 s[20:21], s[40:41]
	s_cbranch_execz .LBB0_1200
	s_waitcnt lgkmcnt(0)
	v_add_f32_e32 v162, v160, v161
	s_lshl_b32 s54, s75, 2
	v_lshlrev_b64 v[160:161], 6, v[180:181]
	s_ashr_i32 s55, s54, 31
	v_lshl_add_u64 v[160:161], s[26:27], 0, v[160:161]
	v_lshl_add_u64 v[160:161], s[54:55], 2, v[160:161]
	s_lshl_b32 s82, s56, 2
	v_lshl_add_u64 v[160:161], v[160:161], 0, s[82:83]
	global_store_dword v[160:161], v162, off
